# nt also on the read-once Q row loads of the sliding-window attention units
# speedup vs baseline: 1.0076x; 1.0076x over previous
.LBB0_919:
	s_or_b64 exec, exec, s[6:7]
	v_readlane_b32 s6, v254, 5
	s_bfe_u32 s46, s6, 0x10006
	v_bfe_u32 v4, v227, 2, 2
	v_and_b32_e32 v5, 16, v226
	s_lshl_b32 s55, s46, 5
	v_lshlrev_b32_e32 v16, 2, v229
	v_lshlrev_b32_e32 v160, 2, v226
	v_or3_b32 v4, v16, v4, s55
	v_and_or_b32 v5, v160, 12, v5
	v_or_b32_e32 v165, 0x80, v205
	s_lshr_b32 s54, s6, 7
	v_lshlrev_b32_e32 v4, 6, v4
	v_lshlrev_b32_e32 v5, 1, v5
	s_add_i32 s6, 0, 0x6c00
	v_add_u32_e32 v96, s9, v165
	v_add3_u32 v164, v5, s6, v4
	s_lshl_b32 s6, s88, 2
	v_lshl_add_u64 v[4:5], s[4:5], 0, v[96:97]
	s_movk_i32 s56, 0xc00
	s_and_b32 s41, s6, 0x7fffff00
	v_mad_u64_u32 v[2:3], s[6:7], v4, s56, v[2:3]
	s_lshl_b32 s9, s89, 5
	v_mad_u32_u24 v3, v5, s56, v3
	v_and_or_b32 v166, s9, 32, v228
	v_mul_f32_e32 v1, 0x413a82f9, v6
	global_load_dwordx4 v[116:119], v[2:3], off offset:2048
	global_load_dwordx4 v[120:123], v[2:3], off offset:2560
	v_or_b32_e32 v2, s8, v166
	v_mul_f32_e32 v1, v1, v7
	v_or_b32_e32 v4, s4, v2
	v_mov_b64_e32 v[2:3], s[0:1]
	s_lshl_b32 s33, s52, 8
	s_and_b32 s57, s9, 0x7fffffc0
	v_min_f32_e32 v163, 0x42c80000, v1
	v_lshrrev_b32_e32 v1, 2, v227
	v_mad_u64_u32 v[2:3], s[6:7], v4, s56, v[2:3]
	v_mov_b32_e32 v167, 0xc00
	s_add_i32 s4, s57, s33
	v_mad_u32_u24 v3, s5, v167, v3
	s_ashr_i32 s5, s4, 31
	v_and_b32_e32 v18, 8, v1
	v_lshl_add_u64 v[2:3], s[4:5], 1, v[2:3]
	v_lshlrev_b32_e32 v96, 1, v18
	v_lshl_add_u64 v[2:3], v[2:3], 0, v[96:97]
	global_load_dwordx4 v[152:155], v[2:3], off nt
	global_load_dwordx4 v[148:151], v[2:3], off offset:32 nt
	global_load_dwordx4 v[144:147], v[2:3], off offset:64 nt
	global_load_dwordx4 v[140:143], v[2:3], off offset:96 nt
	v_or_b32_e32 v22, 2, v16
	v_cmp_gt_u32_e64 s[8:9], v22, v228
	v_or_b32_e32 v22, 3, v16
	v_cmp_gt_u32_e64 s[10:11], v22, v228
	v_or_b32_e32 v22, 8, v16
	v_cmp_gt_u32_e64 s[12:13], v22, v228
	v_or_b32_e32 v22, 9, v16
	v_cmp_gt_u32_e64 s[14:15], v22, v228
	v_or_b32_e32 v22, 10, v16
	v_cmp_gt_u32_e64 s[16:17], v22, v228
	v_or_b32_e32 v22, 11, v16
	v_cmp_gt_u32_e64 s[18:19], v22, v228
	v_or_b32_e32 v22, 16, v16
	v_cmp_gt_u32_e64 s[20:21], v22, v228
	v_or_b32_e32 v22, 17, v16
	v_cmp_gt_u32_e64 s[22:23], v22, v228
	v_or_b32_e32 v22, 18, v16
	v_cmp_gt_u32_e64 s[24:25], v22, v228
	v_or_b32_e32 v22, 19, v16
	v_and_b32_e32 v1, 7, v226
	v_cmp_gt_u32_e64 s[26:27], v22, v228
	v_or_b32_e32 v22, 24, v16
	s_or_b32 s59, s41, s2
	s_and_b32 s2, s88, 32
	s_lshl_b32 s47, s53, 2
	v_lshl_add_u32 v17, v1, 4, 0
	v_bfe_u32 v1, v226, 2, 1
	v_cmp_gt_u32_e64 s[28:29], v22, v228
	v_or_b32_e32 v22, 25, v16
	s_or_b32 s60, s2, s47
	v_mul_u32_u24_e32 v1, 0x3000, v1
	v_and_b32_e32 v161, 48, v192
	s_mul_i32 s4, s46, 0x1200
	v_cmp_gt_u32_e64 s[30:31], v22, v228
	v_or_b32_e32 v22, 26, v16
	s_lshr_b32 s2, s60, 2
	v_add3_u32 v19, 0, v1, v161
	v_mov_b32_e32 v1, v97
	s_add_i32 s4, s4, 0
	v_cmp_gt_u32_e64 s[34:35], v22, v228
	v_or_b32_e32 v22, 27, v16
	s_lshl_b32 s61, s2, 19
	s_lshl_b32 s47, s2, 3
	v_lshl_or_b32 v187, s2, 8, v227
	s_add_i32 s2, s59, s60
	v_lshl_add_u64 v[98:99], s[0:1], 0, v[0:1]
	v_xor_b32_e32 v0, 0x80000000, v163
	v_lshl_add_u32 v20, v229, 4, s4
	v_mul_u32_u24_e32 v21, 0x90, v228
	v_cmp_gt_u32_e64 s[4:5], v16, v228
	v_cmp_lt_u32_e64 s[6:7], v16, v228
	v_cmp_gt_u32_e64 s[36:37], v22, v228
	v_mul_u32_u24_e32 v22, 0x90, v205
	v_lshlrev_b32_e32 v23, 6, v205
	v_mul_u32_u24_e32 v24, 0x90, v162
	v_lshlrev_b32_e32 v25, 6, v162
	v_lshlrev_b32_e32 v26, 6, v165
	s_lshl_b32 s2, s2, 6
	v_lshlrev_b32_e32 v158, 1, v16
	v_mbcnt_lo_u32_b32 v16, -1, 0
	s_mov_b32 s58, 4
	v_mov_b32_e32 v1, v0
	v_mov_b32_e32 v2, v0
	v_mov_b32_e32 v3, v0
	v_mov_b32_e32 v4, v0
	v_mov_b32_e32 v5, v0
	v_mov_b32_e32 v6, v0
	v_mov_b32_e32 v7, v0
	v_mov_b32_e32 v8, v0
	v_mov_b32_e32 v9, v0
	v_mov_b32_e32 v10, v0
	v_mov_b32_e32 v11, v0
	v_mov_b32_e32 v12, v0
	v_mov_b32_e32 v13, v0
	v_mov_b32_e32 v14, v0
	v_mov_b32_e32 v15, v0
	s_waitcnt vmcnt(3)
	v_mov_b64_e32 v[124:125], v[152:153]
	s_waitcnt vmcnt(2)
	v_mov_b64_e32 v[128:129], v[148:149]
	s_waitcnt vmcnt(1)
	v_mov_b64_e32 v[132:133], v[144:145]
	s_waitcnt vmcnt(0)
	v_mov_b64_e32 v[136:137], v[140:141]
	v_add_u32_e32 v168, 0x3000, v164
	v_add_u32_e32 v169, 0x400, v164
	v_add_u32_e32 v170, 0x3400, v164
	v_add_u32_e32 v171, 0x800, v164
	v_add_u32_e32 v172, 0x3800, v164
	v_add_u32_e32 v173, 0xc00, v164
	v_add_u32_e32 v174, 0x3c00, v164
	v_add_u32_e32 v175, 0x1000, v164
	v_add_u32_e32 v176, 0x4000, v164
	v_add_u32_e32 v177, 0x1400, v164
	v_add_u32_e32 v178, 0x4400, v164
	v_add_u32_e32 v179, 0x1800, v164
	v_add_u32_e32 v180, 0x4800, v164
	v_add_u32_e32 v181, 0x1c00, v164
	v_add_u32_e32 v182, 0x4c00, v164
	v_add_u32_e32 v183, 0x2000, v164
	v_add_u32_e32 v184, 0x5000, v164
	v_add_u32_e32 v185, 0x2400, v164
	v_add_u32_e32 v186, 0x5400, v164
	s_lshr_b32 s41, s88, 5
	s_lshl_b32 s62, s46, 16
	s_or_b32 s63, s47, s46
	s_add_i32 s64, s2, 64
	v_add_u32_e32 v188, v17, v22
	v_add_u32_e32 v189, v19, v23
	v_add_u32_e32 v190, v17, v24
	v_add_u32_e32 v191, v19, v25
	v_add_u32_e32 v193, v19, v26
	v_lshlrev_b32_e32 v156, 1, v18
	v_add_u32_e32 v196, v20, v21
	s_mov_b32 s65, 0x3fb8aa3b
	v_mov_b32_e32 v197, 0xff800000
	v_mbcnt_hi_u32_b32 v195, -1, v16
	v_mov_b64_e32 v[126:127], v[154:155]
	v_mov_b64_e32 v[130:131], v[150:151]
	v_mov_b64_e32 v[134:135], v[146:147]
	v_mov_b64_e32 v[138:139], v[142:143]
	s_branch .LBB0_923

.LBB0_928:
	s_or_b64 exec, exec, s[50:51]
	v_add_u32_e32 v96, s69, v165
	v_lshl_add_u64 v[18:19], s[48:49], 0, v[96:97]
	v_mad_u64_u32 v[16:17], s[50:51], v18, s56, v[16:17]
	v_mad_u32_u24 v17, v19, s56, v17
	global_load_dwordx4 v[116:119], v[16:17], off offset:2048
	global_load_dwordx4 v[120:123], v[16:17], off offset:2560
	v_or_b32_e32 v16, s68, v166
	v_or_b32_e32 v18, s48, v16
	v_mov_b64_e32 v[16:17], s[0:1]
	s_lshl_b32 s2, s67, 8
	v_mad_u64_u32 v[16:17], s[50:51], v18, s56, v[16:17]
	s_add_i32 s48, s2, s57
	v_mad_u32_u24 v17, s49, v167, v17
	s_ashr_i32 s49, s48, 31
	v_lshl_add_u64 v[16:17], s[48:49], 1, v[16:17]
	v_mov_b32_e32 v157, v97
	v_lshl_add_u64 v[16:17], v[16:17], 0, v[156:157]
	global_load_dwordx4 v[124:127], v[16:17], off nt
	global_load_dwordx4 v[128:131], v[16:17], off offset:32 nt
	global_load_dwordx4 v[132:135], v[16:17], off offset:64 nt
	global_load_dwordx4 v[136:139], v[16:17], off offset:96 nt
